# P2 epilogue: per-tile bias loads issued at the start of the tile K-loop, vmcnt(0) at the epilogue start dropped
# speedup vs baseline: 1.0111x; 1.0048x over previous
; #define PG8_WAIT_V(n) asm volatile("s_waitcnt vmcnt(" #n ")" ::: "memory")
; #define PG8_BAR __builtin_amdgcn_s_barrier()
; template <class Epi>
; DI void gemm_phase(PG8_LAS unsigned char* lds, const Gemm g, const StaticOrder& S, const Epi& E) {
;     ...
;     for (;;) {
;         const bool has_next = S.next(ui + 1, nxt);
;         const char* nA = has_next ? (const char*)g.A + (size_t)nxt.pm * tstepA + (size_t)nxt.pn * g.a_pn_off : cA; const char* nB = has_next ? (const char*)g.Bt + (size_t)nxt.pn * tstepB : cB;
;         for (int t = 0; t < nt; t += 2) {
;             const bool last = (t == nt - 2);
;             const char* a1 = cA + (size_t)(t + 1) * kstep;
;             const char* a2 = last ? nA : cA + (size_t)(t + 2) * kstep; const char* b2 = last ? nB : cB + (size_t)(t + 2) * kstep;
;             const char* a3 = a2 + kstep; const char* b3 = b2 + kstep;
;             PG8_LDB(B0, 0, 0); PG8_LDB(B1, 0, 1); PG8_SCHED; PG8_LDA(At, 0, 0); PG8_STAGE(PG8_SA(1, 1), a1 + hstepA, voffA);
;             PG8_WAIT_V(8); PG8_WAIT_L(0); PG8_BAR; PG8_MMA(0, 0, At, B0); PG8_MMA(0, 1, At, B1); PG8_BAR; PG8_SCHED;
;             PG8_LDA(At, 0, 1); PG8_STAGE(PG8_SB(0, 0), b2, voffB); PG8_STAGE(PG8_SB(0, 1), b2 + hstepB, voffB); PG8_STAGE(PG8_SA(0, 0), a2, voffA);
;             PG8_WAIT_V(8); PG8_WAIT_L(0); PG8_BAR; PG8_MMA(1, 0, At, B0); PG8_MMA(1, 1, At, B1); PG8_BAR; PG8_SCHED;
;             PG8_LDB(B0, 1, 0); PG8_LDB(B1, 1, 1); PG8_SCHED; PG8_LDA(At, 1, 0); PG8_STAGE(PG8_SA(0, 1), a2 + hstepA, voffA);
;             PG8_WAIT_V(8); PG8_WAIT_L(0); PG8_BAR; PG8_MMA(0, 0, At, B0); PG8_MMA(0, 1, At, B1); PG8_BAR; PG8_SCHED;
;             PG8_LDA(At, 1, 1); PG8_STAGE(PG8_SB(1, 0), b3, voffB); PG8_STAGE(PG8_SB(1, 1), b3 + hstepB, voffB); PG8_STAGE(PG8_SA(1, 0), a3, voffA);
;             PG8_WAIT_V(8); PG8_WAIT_L(0); PG8_BAR; PG8_MMA(1, 0, At, B0); PG8_MMA(1, 1, At, B1); PG8_BAR; PG8_SCHED;
;         }
;         if (wr == 0) PG8_BAR;
;         { int efr = fr, efq = fq; asm volatile("" : "+v"(efr), "+v"(efq)); E(acc, cur, wr, wc, efr, efq); }
;         if (!has_next) break;
; #pragma unroll
;         for (int a = 0; a < 2; ++a)
; #pragma unroll
;             for (int b = 0; b < 2; ++b)
; #pragma unroll
;                 for (int m = 0; m < 4; ++m)
; #pragma unroll
;                     for (int n = 0; n < 2; ++n) acc[a][b][m][n] = (f32x4){0.f, 0.f, 0.f, 0.f};
.LBB0_282:
	v_readlane_b32 s78, v254, 14
	v_readlane_b32 s79, v254, 15
	s_lshl_b32 s74, s27, 8
	s_or_b32 s74, s74, s43
	s_cmp_lt_u32 s27, 8
	s_cselect_b32 s75, 0, 8
	s_add_i32 s74, s74, s75
	v_lshl_add_u32 v244, v171, 3, s74
	v_lshlrev_b32_e32 v244, 2, v244
	s_nop 1
	global_load_dwordx4 v[228:231], v244, s[78:79]
	global_load_dwordx4 v[232:235], v244, s[78:79] offset:16
	global_load_dwordx4 v[236:239], v244, s[78:79] offset:528
	global_load_dwordx4 v[240:243], v244, s[78:79] offset:512
	s_ashr_i32 s17, s16, 31
	s_lshl_b64 s[22:23], s[16:17], 19
	s_add_u32 s22, s94, s22
	s_addc_u32 s23, s95, s23
	s_and_b64 s[24:25], s[0:1], exec
	s_cselect_b32 s6, s23, s29
	s_cselect_b32 s17, s22, s28
	s_ashr_i32 s15, s14, 31
	s_lshl_b64 s[24:25], s[14:15], 19
	s_add_u32 s24, s70, s24
	s_addc_u32 s25, s71, s25
	s_and_b64 s[34:35], s[0:1], exec
	s_cselect_b32 s15, s25, s31
	s_cselect_b32 s50, s24, s30
	s_add_u32 s28, s28, 0x40080
	s_addc_u32 s29, s29, 0
	s_add_u32 s51, s30, 0x100
	v_mov_b32_e32 v0, 0
	s_addc_u32 s52, s31, 0
	s_mov_b32 s53, -2
	v_mov_b32_e32 v1, v0
	v_mov_b32_e32 v2, v0
	v_mov_b32_e32 v3, v0
	v_mov_b32_e32 v4, v0
	v_mov_b32_e32 v5, v0
	v_mov_b32_e32 v6, v0
	v_mov_b32_e32 v7, v0
	v_mov_b32_e32 v16, v0
	v_mov_b32_e32 v17, v0
	v_mov_b32_e32 v18, v0
	v_mov_b32_e32 v19, v0
	v_mov_b32_e32 v20, v0
	v_mov_b32_e32 v21, v0
	v_mov_b32_e32 v22, v0
	v_mov_b32_e32 v23, v0
	v_mov_b32_e32 v32, v0
	v_mov_b32_e32 v33, v0
	v_mov_b32_e32 v34, v0
	v_mov_b32_e32 v35, v0
	v_mov_b32_e32 v36, v0
	v_mov_b32_e32 v37, v0
	v_mov_b32_e32 v38, v0
	v_mov_b32_e32 v39, v0
	v_mov_b32_e32 v48, v0
	v_mov_b32_e32 v49, v0
	v_mov_b32_e32 v50, v0
	v_mov_b32_e32 v51, v0
	v_mov_b32_e32 v52, v0
	v_mov_b32_e32 v53, v0
	v_mov_b32_e32 v54, v0
	v_mov_b32_e32 v55, v0
	v_mov_b32_e32 v8, v0
	v_mov_b32_e32 v9, v0
	v_mov_b32_e32 v10, v0
	v_mov_b32_e32 v11, v0
	v_mov_b32_e32 v12, v0
	v_mov_b32_e32 v13, v0
	v_mov_b32_e32 v14, v0
	v_mov_b32_e32 v15, v0
	v_mov_b32_e32 v24, v0
	v_mov_b32_e32 v25, v0
	v_mov_b32_e32 v26, v0
	v_mov_b32_e32 v27, v0
	v_mov_b32_e32 v28, v0
	v_mov_b32_e32 v29, v0
	v_mov_b32_e32 v30, v0
	v_mov_b32_e32 v31, v0
	v_mov_b32_e32 v40, v0
	v_mov_b32_e32 v41, v0
	v_mov_b32_e32 v42, v0
	v_mov_b32_e32 v43, v0
	v_mov_b32_e32 v44, v0
	v_mov_b32_e32 v45, v0
	v_mov_b32_e32 v46, v0
	v_mov_b32_e32 v47, v0
	v_mov_b32_e32 v56, v0
	v_mov_b32_e32 v57, v0
	v_mov_b32_e32 v58, v0
	v_mov_b32_e32 v59, v0
	v_mov_b32_e32 v60, v0
	v_mov_b32_e32 v61, v0
	v_mov_b32_e32 v62, v0
	v_mov_b32_e32 v63, v0
	v_mov_b32_e32 v64, v0
	v_mov_b32_e32 v65, v0
	v_mov_b32_e32 v66, v0
	v_mov_b32_e32 v67, v0
	v_mov_b32_e32 v68, v0
	v_mov_b32_e32 v69, v0
	v_mov_b32_e32 v70, v0
	v_mov_b32_e32 v71, v0
	v_mov_b32_e32 v80, v0
	v_mov_b32_e32 v81, v0
	v_mov_b32_e32 v82, v0
	v_mov_b32_e32 v83, v0
	v_mov_b32_e32 v84, v0
	v_mov_b32_e32 v85, v0
	v_mov_b32_e32 v86, v0
	v_mov_b32_e32 v87, v0
	v_mov_b32_e32 v104, v0
	v_mov_b32_e32 v105, v0
	v_mov_b32_e32 v106, v0
	v_mov_b32_e32 v107, v0
	v_mov_b32_e32 v108, v0
	v_mov_b32_e32 v109, v0
	v_mov_b32_e32 v110, v0
	v_mov_b32_e32 v111, v0
	v_mov_b32_e32 v128, v0
	v_mov_b32_e32 v129, v0
	v_mov_b32_e32 v130, v0
	v_mov_b32_e32 v131, v0
	v_mov_b32_e32 v132, v0
	v_mov_b32_e32 v133, v0
	v_mov_b32_e32 v134, v0
	v_mov_b32_e32 v135, v0
	v_mov_b32_e32 v72, v0
	v_mov_b32_e32 v73, v0
	v_mov_b32_e32 v74, v0
	v_mov_b32_e32 v75, v0
	v_mov_b32_e32 v76, v0
	v_mov_b32_e32 v77, v0
	v_mov_b32_e32 v78, v0
	v_mov_b32_e32 v79, v0
	v_mov_b32_e32 v88, v0
	v_mov_b32_e32 v89, v0
	v_mov_b32_e32 v90, v0
	v_mov_b32_e32 v91, v0
	v_mov_b32_e32 v100, v0
	v_mov_b32_e32 v101, v0
	v_mov_b32_e32 v102, v0
	v_mov_b32_e32 v103, v0
	v_mov_b32_e32 v120, v0
	v_mov_b32_e32 v121, v0
	v_mov_b32_e32 v122, v0
	v_mov_b32_e32 v123, v0
	v_mov_b32_e32 v124, v0
	v_mov_b32_e32 v125, v0
	v_mov_b32_e32 v126, v0
	v_mov_b32_e32 v127, v0
	v_mov_b32_e32 v136, v0
	v_mov_b32_e32 v137, v0
	v_mov_b32_e32 v138, v0
	v_mov_b32_e32 v139, v0
	v_mov_b32_e32 v140, v0
	v_mov_b32_e32 v141, v0
	v_mov_b32_e32 v142, v0
	v_mov_b32_e32 v143, v0

;     DI void operator()(const f32x4 (&acc)[2][2][4][2], const pg8::Unit& u, int wr, int wc, int fr, int fq) const {
;         const int pn = u.pn;
;         int boff, c0, slot;
;         if (pn < 4) { boff = 0; c0 = 0; slot = 0; }
;         else if (pn < 8) { boff = 1024; c0 = 1024; slot = 0; }
;         else if (pn < 10) { boff = 2056; c0 = 2048; slot = 0; }
;         else if (pn < 14) { boff = 2568; c0 = 2560; slot = 1; }
;         else { boff = 3592; c0 = 3584; slot = 2; }
;         const int colb = pn * 256 + wc * 32 + 8 * fq - c0;
;         f32x4 bia[2][2];
; #pragma unroll
;         for (int bj = 0; bj < 2; ++bj) { bia[bj][0] = *(const f32x4*)(bin + boff + colb + bj * 128); bia[bj][1] = *(const f32x4*)(bin + boff + colb + bj * 128 + 4); }
;         const int t0 = u.pm * 256 + wr * 64 + fr;
;         if (pn < 4) {
; #pragma unroll
;             for (int i = 0; i < 16; ++i) {
;                 const int ai = TILE_AI(i), m = TILE_M(i), bj = TILE_BJ(i);
;                 const int t = t0 + ai * 128 + m * 16, col = colb + bj * 128;
;                 const f32x4 v0 = acc[ai][bj][m][0] + bia[bj][0], v1 = acc[ai][bj][m][1] + bia[bj][1];
.LBB0_293:
	s_lshl_b32 s6, s27, 8
	s_or_b32 s6, s6, s43
	v_lshlrev_b32_e32 v152, 3, v92
	v_readlane_b32 s72, v254, 4
	v_add_u32_e32 v177, s6, v152
	s_lshl_b32 s6, s34, 2
	v_readlane_b32 s82, v254, 14
	v_add_u32_e32 v164, s15, v177
	v_readlane_b32 s83, v254, 15
	s_add_u32 s34, s82, s6
	s_addc_u32 s35, s83, 0
	v_ashrrev_i32_e32 v165, 31, v164
	v_lshl_add_u64 v[96:97], v[164:165], 2, s[34:35]
	v_mov_b64_e32 v[116:117], v[228:229]
	v_mov_b64_e32 v[118:119], v[230:231]
	v_mov_b64_e32 v[112:113], v[232:233]
	v_mov_b64_e32 v[114:115], v[234:235]
	v_mov_b64_e32 v[92:93], v[236:237]
	v_mov_b64_e32 v[94:95], v[238:239]
	s_nop 0
	v_mov_b64_e32 v[96:97], v[240:241]
	v_mov_b64_e32 v[98:99], v[242:243]
	v_readlane_b32 s73, v254, 5
	s_lshl_b32 s6, s26, 8
	s_add_i32 s6, s6, s42
	v_readlane_b32 s72, v254, 58
	s_mov_b64 s[34:35], -1
	s_and_b64 vcc, exec, s[28:29]
	v_add_u32_e32 v162, s6, v176
	v_readlane_b32 s73, v254, 59
	v_readlane_b32 s74, v254, 6
	v_readlane_b32 s75, v254, 7
	v_readlane_b32 s76, v254, 8
	v_readlane_b32 s77, v254, 9
	v_readlane_b32 s78, v254, 10
	v_readlane_b32 s79, v254, 11
	v_readlane_b32 s80, v254, 12
	v_readlane_b32 s81, v254, 13
	v_readlane_b32 s84, v254, 16
	v_readlane_b32 s85, v254, 17
	v_readlane_b32 s86, v254, 18
	v_readlane_b32 s87, v254, 19
	s_nop 0
	v_pk_add_f32 v[142:143], v[142:143], v[118:119]
	v_pk_add_f32 v[140:141], v[140:141], v[116:117]
	v_pk_add_f32 v[138:139], v[138:139], v[114:115]
	v_pk_add_f32 v[136:137], v[136:137], v[112:113]
	s_cbranch_vccnz .LBB0_296
	s_andn2_b64 vcc, exec, s[34:35]
	s_cbranch_vccz .LBB0_301
